# GEMM2 (both layers) converted to pair-tile LDS-DMA mainloop; A operand read row-major from PROJ with per-lane swizzled source addresses
# speedup vs baseline: 1.0367x; 1.0088x over previous
.LBB0_493:
	s_or_b64 exec, exec, s[2:3]
	s_add_u32 s0, s48, 0xa80000
	s_addc_u32 s1, s49, 0
	v_mov_b32_e32 v150, v148
	s_mov_b32 s4, s55
	s_waitcnt lgkmcnt(0)
	s_barrier
	v_writelane_b32 v158, s0, 24
	s_mov_b32 s5, s94
	s_cmpk_gt_i32 s4, 0x827
	v_writelane_b32 v158, s1, 25
	s_cbranch_scc1 .LBB0_522
	v_ashrrev_i32_e32 v151, 2, v150
	v_lshlrev_b32_e32 v0, 4, v150
	v_and_b32_e32 v128, 48, v0
	v_lshlrev_b32_e32 v0, 5, v151
	v_ashrrev_i32_e32 v1, 31, v0
	v_readlane_b32 s0, v158, 24
	v_mov_b32_e32 v131, 0
	v_lshlrev_b64 v[0:1], 1, v[0:1]
	v_readlane_b32 s1, v158, 25
	v_mov_b32_e32 v129, v131
	v_and_b32_e32 v5, 31, v150
	v_lshl_add_u64 v[2:3], s[0:1], 0, v[0:1]
	v_lshl_add_u64 v[134:135], v[2:3], 0, v[128:129]
	v_lshrrev_b32_e32 v3, 1, v150
	s_mov_b32 s1, 0xfffffc0
	s_movk_i32 s0, 0x50
	v_and_b32_e32 v4, 16, v3
	v_and_or_b32 v3, v3, s1, v5
	v_and_b32_e32 v5, 0x5f, v150
	v_mul_lo_u32 v2, v151, s0
	v_mul_lo_u32 v3, v3, s0
	v_mul_u32_u24_e32 v5, 0x50, v5
	s_add_u32 s0, s90, 0x22aa00
	v_lshl_add_u64 v[132:133], s[46:47], 0, v[128:129]
	s_addc_u32 s1, s91, 0
	v_lshl_add_u64 v[136:137], s[48:49], 0, v[0:1]
	s_movk_i32 s6, 0x2a00
	v_mov_b32_e32 v152, 0x60000
	s_mov_b32 s7, 0xa8000
	v_add_u32_e32 v153, v2, v128
	v_mov_b64_e32 v[138:139], s[46:47]
	v_add_u32_e32 v154, v4, v3
	v_add_u32_e32 v155, v4, v5
	s_movk_i32 s8, 0x210
	v_and_b32_e32 v76, 63, v148
	v_lshrrev_b32_e32 v77, 6, v148
	v_and_b32_e32 v130, 31, v76
	v_lshlrev_b32_e32 v130, 6, v130
	v_lshrrev_b32_e32 v64, 5, v76
	v_bfe_u32 v65, v76, 2, 2
	v_xor_b32_e32 v64, v64, v65
	v_lshl_add_u32 v130, v64, 4, v130
	v_lshrrev_b32_e32 v64, 1, v77
	v_lshl_add_u32 v151, v64, 12, v130
	v_and_b32_e32 v64, 1, v77
	v_lshl_add_u32 v157, v64, 12, v130
	v_xor_b32_e32 v156, 32, v151
	v_xor_b32_e32 v164, 32, v157
	v_lshrrev_b32_e32 v130, 2, v76
	v_lshlrev_b32_e32 v130, 6, v130
	v_and_b32_e32 v64, 3, v76
	v_bfe_u32 v65, v76, 4, 2
	v_xor_b32_e32 v64, v64, v65
	v_lshl_add_u32 v130, v64, 4, v130
	v_lshl_add_u32 v165, v77, 11, v130
	v_lshrrev_b32_e32 v130, 2, v76
	v_lshl_add_u32 v130, v77, 5, v130
	v_mul_u32_u24_e32 v130, 0x2a00, v130
	v_and_b32_e32 v64, 3, v76
	v_bfe_u32 v65, v76, 4, 2
	v_xor_b32_e32 v64, v64, v65
	v_lshl_add_u32 v166, v64, 4, v130
	v_add_u32_e32 v167, 0x2a000, v166
	v_readfirstlane_b32 s28, v77
	s_lshl_b32 s28, s28, 11
	s_and_b32 s33, s4, 7
	s_lshr_b32 s4, s4, 3
	s_lshr_b32 s56, s5, 3
	s_sub_u32 s57, 268, s33
	s_lshr_b32 s57, s57, 3
	s_mul_i32 s57, s57, 4
	s_branch .Lg2a_hdr
.LBB0_495:
	s_or_b64 exec, exec, s[2:3]
	s_cmp_eq_u32 s32, 0
	s_cbranch_scc1 .Lg2a_pass2
	s_add_i32 s4, s4, s56
	s_cmp_lt_u32 s4, s57
	s_cbranch_scc0 .LBB0_522
	s_branch .Lg2a_hdr
.Lg2a_pass2:
	s_mov_b32 s32, 1
	v_mov_b32_e32 v48, v78
	v_mov_b32_e32 v49, v79
	v_mov_b32_e32 v50, v80
	v_mov_b32_e32 v51, v81
	v_mov_b32_e32 v52, v82
	v_mov_b32_e32 v53, v83
	v_mov_b32_e32 v54, v84
	v_mov_b32_e32 v55, v85
	v_mov_b32_e32 v56, v86
	v_mov_b32_e32 v57, v87
	v_mov_b32_e32 v58, v88
	v_mov_b32_e32 v59, v89
	v_mov_b32_e32 v60, v90
	v_mov_b32_e32 v61, v91
	v_mov_b32_e32 v62, v92
	v_mov_b32_e32 v63, v93
	v_mov_b32_e32 v32, v94
	v_mov_b32_e32 v33, v95
	v_mov_b32_e32 v34, v96
	v_mov_b32_e32 v35, v97
	v_mov_b32_e32 v36, v98
	v_mov_b32_e32 v37, v99
	v_mov_b32_e32 v38, v100
	v_mov_b32_e32 v39, v101
	v_mov_b32_e32 v40, v102
	v_mov_b32_e32 v41, v103
	v_mov_b32_e32 v42, v104
	v_mov_b32_e32 v43, v105
	v_mov_b32_e32 v44, v106
	v_mov_b32_e32 v45, v107
	v_mov_b32_e32 v46, v108
	v_mov_b32_e32 v47, v109
	v_mov_b32_e32 v16, v110
	v_mov_b32_e32 v17, v111
	v_mov_b32_e32 v18, v112
	v_mov_b32_e32 v19, v113
	v_mov_b32_e32 v20, v114
	v_mov_b32_e32 v21, v115
	v_mov_b32_e32 v22, v116
	v_mov_b32_e32 v23, v117
	v_mov_b32_e32 v24, v118
	v_mov_b32_e32 v25, v119
	v_mov_b32_e32 v26, v120
	v_mov_b32_e32 v27, v121
	v_mov_b32_e32 v28, v122
	v_mov_b32_e32 v29, v123
	v_mov_b32_e32 v30, v124
	v_mov_b32_e32 v31, v125
	v_mov_b32_e32 v0, v132
	v_mov_b32_e32 v1, v133
	v_mov_b32_e32 v2, v134
	v_mov_b32_e32 v3, v135
	v_mov_b32_e32 v4, v136
	v_mov_b32_e32 v5, v137
	v_mov_b32_e32 v6, v138
	v_mov_b32_e32 v7, v139
	v_mov_b32_e32 v8, v140
	v_mov_b32_e32 v9, v141
	v_mov_b32_e32 v10, v142
	v_mov_b32_e32 v11, v143
	v_mov_b32_e32 v12, v144
	v_mov_b32_e32 v13, v145
	v_mov_b32_e32 v14, v146
	v_mov_b32_e32 v15, v147
	s_lshl_b32 s9, s30, 7
	s_add_i32 s10, s31, 1
	s_branch .Lg2a_epi
.Lg2a_hdr:
	s_cmp_ge_u32 s4, 128
	s_cbranch_scc1 .Lg2a_lastgrp
	s_mul_hi_u32 s2, s4, 0x4000000
	s_mul_i32 s3, s2, 64
	s_sub_i32 s3, s4, s3
	s_lshr_b32 s11, s3, 4
	s_and_b32 s7, s3, 15
	s_lshl4_add_u32 s7, s2, s7
	s_branch .Lg2a_cont
.Lg2a_lastgrp:
	s_sub_u32 s3, s4, 128
	s_mul_hi_u32 s2, s3, 0x40000000
	s_mul_i32 s11, s2, 4
	s_sub_i32 s11, s3, s11
	s_add_u32 s7, s2, 32
.Lg2a_cont:
	s_lshl3_add_u32 s30, s7, s33
	s_lshl_b32 s31, s11, 1
	s_mul_i32 s2, s30, 0x150000
	s_add_u32 s22, s46, s2
	s_addc_u32 s23, s47, 0
	s_mul_i32 s2, s31, 0x60000
	s_add_u32 s2, s2, 0xa80000
	s_add_u32 s24, s48, s2
	s_addc_u32 s25, s49, 0
	s_add_u32 s26, s24, 0x60000
	s_addc_u32 s27, s25, 0
	s_waitcnt vmcnt(0) lgkmcnt(0)
	s_barrier
	s_add_u32 m0, s28, 0x0
	s_nop 0
	global_load_lds_dwordx4 v166, s[22:23]
	s_add_u32 m0, s28, 0x400
	s_nop 0
	global_load_lds_dwordx4 v167, s[22:23]
	s_add_u32 s22, s22, 64
	s_addc_u32 s23, s23, 0
	s_add_u32 m0, s28, 0x2000
	s_nop 0
	global_load_lds_dwordx4 v165, s[24:25]
	global_load_lds_dwordx4 v165, s[24:25] offset:1024
	s_add_u32 s24, s24, 0x2000
	s_addc_u32 s25, s25, 0
	s_add_u32 m0, s28, 0x4000
	s_nop 0
	global_load_lds_dwordx4 v165, s[26:27]
	global_load_lds_dwordx4 v165, s[26:27] offset:1024
	s_add_u32 s26, s26, 0x2000
	s_addc_u32 s27, s27, 0
	s_waitcnt vmcnt(0)
	s_barrier
	s_add_u32 m0, s28, 0x6000
	s_nop 0
	global_load_lds_dwordx4 v166, s[22:23]
	s_add_u32 m0, s28, 0x6400
	s_nop 0
	global_load_lds_dwordx4 v167, s[22:23]
	s_add_u32 s22, s22, 64
	s_addc_u32 s23, s23, 0
	s_add_u32 m0, s28, 0x8000
	s_nop 0
	global_load_lds_dwordx4 v165, s[24:25]
	global_load_lds_dwordx4 v165, s[24:25] offset:1024
	s_add_u32 s24, s24, 0x2000
	s_addc_u32 s25, s25, 0
	s_add_u32 m0, s28, 0xa400
	s_nop 0
	global_load_lds_dwordx4 v165, s[26:27]
	global_load_lds_dwordx4 v165, s[26:27] offset:1024
	s_add_u32 s26, s26, 0x2000
	s_addc_u32 s27, s27, 0
	ds_read_b128 v[64:67], v151 offset:0
	ds_read_b128 v[72:75], v157 offset:8192
	ds_read_b128 v[126:129], v157 offset:10240
	ds_read_b128 v[152:155], v157 offset:16384
	ds_read_b128 v[160:163], v157 offset:18432
	ds_read_b128 v[68:71], v151 offset:2048
	s_waitcnt lgkmcnt(4)
	v_mfma_f32_32x32x16_bf16 v[48:63], v[64:67], v[72:75], 0
	s_waitcnt lgkmcnt(3)
	v_mfma_f32_32x32x16_bf16 v[32:47], v[64:67], v[126:129], 0
	s_waitcnt lgkmcnt(2)
	v_mfma_f32_32x32x16_bf16 v[78:93], v[64:67], v[152:155], 0
	s_waitcnt lgkmcnt(1)
	v_mfma_f32_32x32x16_bf16 v[94:109], v[64:67], v[160:163], 0
	ds_read_b128 v[64:67], v156 offset:0
	s_waitcnt lgkmcnt(1)
	v_mfma_f32_32x32x16_bf16 v[132:147], v[68:71], v[160:163], 0
	ds_read_b128 v[160:163], v164 offset:18432
	v_mfma_f32_32x32x16_bf16 v[110:125], v[68:71], v[152:155], 0
	ds_read_b128 v[152:155], v164 offset:16384
	v_mfma_f32_32x32x16_bf16 v[0:15], v[68:71], v[126:129], 0
	ds_read_b128 v[126:129], v164 offset:10240
	v_mfma_f32_32x32x16_bf16 v[16:31], v[68:71], v[72:75], 0
	ds_read_b128 v[72:75], v164 offset:8192
	ds_read_b128 v[68:71], v156 offset:2048
	s_waitcnt lgkmcnt(4)
	v_mfma_f32_32x32x16_bf16 v[94:109], v[64:67], v[160:163], v[94:109]
	s_waitcnt lgkmcnt(3)
	v_mfma_f32_32x32x16_bf16 v[78:93], v[64:67], v[152:155], v[78:93]
	s_waitcnt lgkmcnt(2)
	v_mfma_f32_32x32x16_bf16 v[32:47], v[64:67], v[126:129], v[32:47]
	s_waitcnt lgkmcnt(1)
	v_mfma_f32_32x32x16_bf16 v[48:63], v[64:67], v[72:75], v[48:63]
	s_waitcnt vmcnt(0) lgkmcnt(0)
	s_barrier
	ds_read_b128 v[64:67], v151 offset:24576
	s_add_u32 m0, s28, 0x0
	s_nop 0
	global_load_lds_dwordx4 v166, s[22:23]
	s_add_u32 m0, s28, 0x400
	s_nop 0
	global_load_lds_dwordx4 v167, s[22:23]
	s_add_u32 s22, s22, 64
	s_addc_u32 s23, s23, 0
	v_mfma_f32_32x32x16_bf16 v[16:31], v[68:71], v[72:75], v[16:31]
	ds_read_b128 v[72:75], v157 offset:32768
	s_add_u32 m0, s28, 0x2000
	s_nop 0
	global_load_lds_dwordx4 v165, s[24:25]
	global_load_lds_dwordx4 v165, s[24:25] offset:1024
	s_add_u32 s24, s24, 0x2000
	s_addc_u32 s25, s25, 0
	v_mfma_f32_32x32x16_bf16 v[0:15], v[68:71], v[126:129], v[0:15]
	ds_read_b128 v[126:129], v157 offset:34816
	s_add_u32 m0, s28, 0x4000
	s_nop 0
	global_load_lds_dwordx4 v165, s[26:27]
	global_load_lds_dwordx4 v165, s[26:27] offset:1024
	s_add_u32 s26, s26, 0x2000
	s_addc_u32 s27, s27, 0
	v_mfma_f32_32x32x16_bf16 v[110:125], v[68:71], v[152:155], v[110:125]
	ds_read_b128 v[152:155], v157 offset:41984
	v_mfma_f32_32x32x16_bf16 v[132:147], v[68:71], v[160:163], v[132:147]
	ds_read_b128 v[160:163], v157 offset:44032
	ds_read_b128 v[68:71], v151 offset:26624
	s_waitcnt lgkmcnt(4)
	v_mfma_f32_32x32x16_bf16 v[48:63], v[64:67], v[72:75], v[48:63]
	s_waitcnt lgkmcnt(3)
	v_mfma_f32_32x32x16_bf16 v[32:47], v[64:67], v[126:129], v[32:47]
	s_waitcnt lgkmcnt(2)
	v_mfma_f32_32x32x16_bf16 v[78:93], v[64:67], v[152:155], v[78:93]
	s_waitcnt lgkmcnt(1)
	v_mfma_f32_32x32x16_bf16 v[94:109], v[64:67], v[160:163], v[94:109]
	ds_read_b128 v[64:67], v156 offset:24576
	s_waitcnt lgkmcnt(1)
	v_mfma_f32_32x32x16_bf16 v[132:147], v[68:71], v[160:163], v[132:147]
	ds_read_b128 v[160:163], v164 offset:44032
	v_mfma_f32_32x32x16_bf16 v[110:125], v[68:71], v[152:155], v[110:125]
	ds_read_b128 v[152:155], v164 offset:41984
	v_mfma_f32_32x32x16_bf16 v[0:15], v[68:71], v[126:129], v[0:15]
	ds_read_b128 v[126:129], v164 offset:34816
	v_mfma_f32_32x32x16_bf16 v[16:31], v[68:71], v[72:75], v[16:31]
	ds_read_b128 v[72:75], v164 offset:32768
	ds_read_b128 v[68:71], v156 offset:26624
	s_waitcnt lgkmcnt(4)
	v_mfma_f32_32x32x16_bf16 v[94:109], v[64:67], v[160:163], v[94:109]
	s_waitcnt lgkmcnt(3)
	v_mfma_f32_32x32x16_bf16 v[78:93], v[64:67], v[152:155], v[78:93]
	s_waitcnt lgkmcnt(2)
	v_mfma_f32_32x32x16_bf16 v[32:47], v[64:67], v[126:129], v[32:47]
	s_waitcnt lgkmcnt(1)
	v_mfma_f32_32x32x16_bf16 v[48:63], v[64:67], v[72:75], v[48:63]
	s_waitcnt vmcnt(0) lgkmcnt(0)
	s_barrier
	ds_read_b128 v[64:67], v151 offset:0
	s_add_u32 m0, s28, 0x6000
	s_nop 0
	global_load_lds_dwordx4 v166, s[22:23]
	s_add_u32 m0, s28, 0x6400
	s_nop 0
	global_load_lds_dwordx4 v167, s[22:23]
	s_add_u32 s22, s22, 64
	s_addc_u32 s23, s23, 0
	v_mfma_f32_32x32x16_bf16 v[16:31], v[68:71], v[72:75], v[16:31]
	ds_read_b128 v[72:75], v157 offset:8192
	s_add_u32 m0, s28, 0x8000
	s_nop 0
	global_load_lds_dwordx4 v165, s[24:25]
	global_load_lds_dwordx4 v165, s[24:25] offset:1024
	s_add_u32 s24, s24, 0x2000
	s_addc_u32 s25, s25, 0
	v_mfma_f32_32x32x16_bf16 v[0:15], v[68:71], v[126:129], v[0:15]
	ds_read_b128 v[126:129], v157 offset:10240
	s_add_u32 m0, s28, 0xa400
	s_nop 0
	global_load_lds_dwordx4 v165, s[26:27]
	global_load_lds_dwordx4 v165, s[26:27] offset:1024
	s_add_u32 s26, s26, 0x2000
	s_addc_u32 s27, s27, 0
	v_mfma_f32_32x32x16_bf16 v[110:125], v[68:71], v[152:155], v[110:125]
	ds_read_b128 v[152:155], v157 offset:16384
	v_mfma_f32_32x32x16_bf16 v[132:147], v[68:71], v[160:163], v[132:147]
	ds_read_b128 v[160:163], v157 offset:18432
	ds_read_b128 v[68:71], v151 offset:2048
	s_mov_b32 s29, 22
.Lg2a_kloop:
	s_waitcnt lgkmcnt(4)
	v_mfma_f32_32x32x16_bf16 v[48:63], v[64:67], v[72:75], v[48:63]
	s_waitcnt lgkmcnt(3)
	v_mfma_f32_32x32x16_bf16 v[32:47], v[64:67], v[126:129], v[32:47]
	s_waitcnt lgkmcnt(2)
	v_mfma_f32_32x32x16_bf16 v[78:93], v[64:67], v[152:155], v[78:93]
	s_waitcnt lgkmcnt(1)
	v_mfma_f32_32x32x16_bf16 v[94:109], v[64:67], v[160:163], v[94:109]
	ds_read_b128 v[64:67], v156 offset:0
	s_waitcnt lgkmcnt(1)
	v_mfma_f32_32x32x16_bf16 v[132:147], v[68:71], v[160:163], v[132:147]
	ds_read_b128 v[160:163], v164 offset:18432
	v_mfma_f32_32x32x16_bf16 v[110:125], v[68:71], v[152:155], v[110:125]
	ds_read_b128 v[152:155], v164 offset:16384
	v_mfma_f32_32x32x16_bf16 v[0:15], v[68:71], v[126:129], v[0:15]
	ds_read_b128 v[126:129], v164 offset:10240
	v_mfma_f32_32x32x16_bf16 v[16:31], v[68:71], v[72:75], v[16:31]
	ds_read_b128 v[72:75], v164 offset:8192
	ds_read_b128 v[68:71], v156 offset:2048
	s_waitcnt lgkmcnt(4)
	v_mfma_f32_32x32x16_bf16 v[94:109], v[64:67], v[160:163], v[94:109]
	s_waitcnt lgkmcnt(3)
	v_mfma_f32_32x32x16_bf16 v[78:93], v[64:67], v[152:155], v[78:93]
	s_waitcnt lgkmcnt(2)
	v_mfma_f32_32x32x16_bf16 v[32:47], v[64:67], v[126:129], v[32:47]
	s_waitcnt lgkmcnt(1)
	v_mfma_f32_32x32x16_bf16 v[48:63], v[64:67], v[72:75], v[48:63]
	s_waitcnt vmcnt(0) lgkmcnt(0)
	s_barrier
	ds_read_b128 v[64:67], v151 offset:24576
	s_add_u32 m0, s28, 0x0
	s_nop 0
	global_load_lds_dwordx4 v166, s[22:23]
	s_add_u32 m0, s28, 0x400
	s_nop 0
	global_load_lds_dwordx4 v167, s[22:23]
	s_add_u32 s22, s22, 64
	s_addc_u32 s23, s23, 0
	v_mfma_f32_32x32x16_bf16 v[16:31], v[68:71], v[72:75], v[16:31]
	ds_read_b128 v[72:75], v157 offset:32768
	s_add_u32 m0, s28, 0x2000
	s_nop 0
	global_load_lds_dwordx4 v165, s[24:25]
	global_load_lds_dwordx4 v165, s[24:25] offset:1024
	s_add_u32 s24, s24, 0x2000
	s_addc_u32 s25, s25, 0
	v_mfma_f32_32x32x16_bf16 v[0:15], v[68:71], v[126:129], v[0:15]
	ds_read_b128 v[126:129], v157 offset:34816
	s_add_u32 m0, s28, 0x4000
	s_nop 0
	global_load_lds_dwordx4 v165, s[26:27]
	global_load_lds_dwordx4 v165, s[26:27] offset:1024
	s_add_u32 s26, s26, 0x2000
	s_addc_u32 s27, s27, 0
	v_mfma_f32_32x32x16_bf16 v[110:125], v[68:71], v[152:155], v[110:125]
	ds_read_b128 v[152:155], v157 offset:41984
	v_mfma_f32_32x32x16_bf16 v[132:147], v[68:71], v[160:163], v[132:147]
	ds_read_b128 v[160:163], v157 offset:44032
	ds_read_b128 v[68:71], v151 offset:26624
	s_waitcnt lgkmcnt(4)
	v_mfma_f32_32x32x16_bf16 v[48:63], v[64:67], v[72:75], v[48:63]
	s_waitcnt lgkmcnt(3)
	v_mfma_f32_32x32x16_bf16 v[32:47], v[64:67], v[126:129], v[32:47]
	s_waitcnt lgkmcnt(2)
	v_mfma_f32_32x32x16_bf16 v[78:93], v[64:67], v[152:155], v[78:93]
	s_waitcnt lgkmcnt(1)
	v_mfma_f32_32x32x16_bf16 v[94:109], v[64:67], v[160:163], v[94:109]
	ds_read_b128 v[64:67], v156 offset:24576
	s_waitcnt lgkmcnt(1)
	v_mfma_f32_32x32x16_bf16 v[132:147], v[68:71], v[160:163], v[132:147]
	ds_read_b128 v[160:163], v164 offset:44032
	v_mfma_f32_32x32x16_bf16 v[110:125], v[68:71], v[152:155], v[110:125]
	ds_read_b128 v[152:155], v164 offset:41984
	v_mfma_f32_32x32x16_bf16 v[0:15], v[68:71], v[126:129], v[0:15]
	ds_read_b128 v[126:129], v164 offset:34816
	v_mfma_f32_32x32x16_bf16 v[16:31], v[68:71], v[72:75], v[16:31]
	ds_read_b128 v[72:75], v164 offset:32768
	ds_read_b128 v[68:71], v156 offset:26624
	s_waitcnt lgkmcnt(4)
	v_mfma_f32_32x32x16_bf16 v[94:109], v[64:67], v[160:163], v[94:109]
	s_waitcnt lgkmcnt(3)
	v_mfma_f32_32x32x16_bf16 v[78:93], v[64:67], v[152:155], v[78:93]
	s_waitcnt lgkmcnt(2)
	v_mfma_f32_32x32x16_bf16 v[32:47], v[64:67], v[126:129], v[32:47]
	s_waitcnt lgkmcnt(1)
	v_mfma_f32_32x32x16_bf16 v[48:63], v[64:67], v[72:75], v[48:63]
	s_waitcnt vmcnt(0) lgkmcnt(0)
	s_barrier
	ds_read_b128 v[64:67], v151 offset:0
	s_add_u32 m0, s28, 0x6000
	s_nop 0
	global_load_lds_dwordx4 v166, s[22:23]
	s_add_u32 m0, s28, 0x6400
	s_nop 0
	global_load_lds_dwordx4 v167, s[22:23]
	s_add_u32 s22, s22, 64
	s_addc_u32 s23, s23, 0
	v_mfma_f32_32x32x16_bf16 v[16:31], v[68:71], v[72:75], v[16:31]
	ds_read_b128 v[72:75], v157 offset:8192
	s_add_u32 m0, s28, 0x8000
	s_nop 0
	global_load_lds_dwordx4 v165, s[24:25]
	global_load_lds_dwordx4 v165, s[24:25] offset:1024
	s_add_u32 s24, s24, 0x2000
	s_addc_u32 s25, s25, 0
	v_mfma_f32_32x32x16_bf16 v[0:15], v[68:71], v[126:129], v[0:15]
	ds_read_b128 v[126:129], v157 offset:10240
	s_add_u32 m0, s28, 0xa400
	s_nop 0
	global_load_lds_dwordx4 v165, s[26:27]
	global_load_lds_dwordx4 v165, s[26:27] offset:1024
	s_add_u32 s26, s26, 0x2000
	s_addc_u32 s27, s27, 0
	v_mfma_f32_32x32x16_bf16 v[110:125], v[68:71], v[152:155], v[110:125]
	ds_read_b128 v[152:155], v157 offset:16384
	v_mfma_f32_32x32x16_bf16 v[132:147], v[68:71], v[160:163], v[132:147]
	ds_read_b128 v[160:163], v157 offset:18432
	ds_read_b128 v[68:71], v151 offset:2048
	s_sub_u32 s29, s29, 1
	s_cmp_lg_u32 s29, 0
	s_cbranch_scc1 .Lg2a_kloop
	s_waitcnt lgkmcnt(4)
	v_mfma_f32_32x32x16_bf16 v[48:63], v[64:67], v[72:75], v[48:63]
	s_waitcnt lgkmcnt(3)
	v_mfma_f32_32x32x16_bf16 v[32:47], v[64:67], v[126:129], v[32:47]
	s_waitcnt lgkmcnt(2)
	v_mfma_f32_32x32x16_bf16 v[78:93], v[64:67], v[152:155], v[78:93]
	s_waitcnt lgkmcnt(1)
	v_mfma_f32_32x32x16_bf16 v[94:109], v[64:67], v[160:163], v[94:109]
	ds_read_b128 v[64:67], v156 offset:0
	s_waitcnt lgkmcnt(1)
	v_mfma_f32_32x32x16_bf16 v[132:147], v[68:71], v[160:163], v[132:147]
	ds_read_b128 v[160:163], v164 offset:18432
	v_mfma_f32_32x32x16_bf16 v[110:125], v[68:71], v[152:155], v[110:125]
	ds_read_b128 v[152:155], v164 offset:16384
	v_mfma_f32_32x32x16_bf16 v[0:15], v[68:71], v[126:129], v[0:15]
	ds_read_b128 v[126:129], v164 offset:10240
	v_mfma_f32_32x32x16_bf16 v[16:31], v[68:71], v[72:75], v[16:31]
	ds_read_b128 v[72:75], v164 offset:8192
	ds_read_b128 v[68:71], v156 offset:2048
	s_waitcnt lgkmcnt(4)
	v_mfma_f32_32x32x16_bf16 v[94:109], v[64:67], v[160:163], v[94:109]
	s_waitcnt lgkmcnt(3)
	v_mfma_f32_32x32x16_bf16 v[78:93], v[64:67], v[152:155], v[78:93]
	s_waitcnt lgkmcnt(2)
	v_mfma_f32_32x32x16_bf16 v[32:47], v[64:67], v[126:129], v[32:47]
	s_waitcnt lgkmcnt(1)
	v_mfma_f32_32x32x16_bf16 v[48:63], v[64:67], v[72:75], v[48:63]
	s_waitcnt vmcnt(0) lgkmcnt(0)
	s_barrier
	ds_read_b128 v[64:67], v151 offset:24576
	v_mfma_f32_32x32x16_bf16 v[16:31], v[68:71], v[72:75], v[16:31]
	ds_read_b128 v[72:75], v157 offset:32768
	v_mfma_f32_32x32x16_bf16 v[0:15], v[68:71], v[126:129], v[0:15]
	ds_read_b128 v[126:129], v157 offset:34816
	v_mfma_f32_32x32x16_bf16 v[110:125], v[68:71], v[152:155], v[110:125]
	ds_read_b128 v[152:155], v157 offset:41984
	v_mfma_f32_32x32x16_bf16 v[132:147], v[68:71], v[160:163], v[132:147]
	ds_read_b128 v[160:163], v157 offset:44032
	ds_read_b128 v[68:71], v151 offset:26624
	s_waitcnt lgkmcnt(4)
	v_mfma_f32_32x32x16_bf16 v[48:63], v[64:67], v[72:75], v[48:63]
	s_waitcnt lgkmcnt(3)
	v_mfma_f32_32x32x16_bf16 v[32:47], v[64:67], v[126:129], v[32:47]
	s_waitcnt lgkmcnt(2)
	v_mfma_f32_32x32x16_bf16 v[78:93], v[64:67], v[152:155], v[78:93]
	s_waitcnt lgkmcnt(1)
	v_mfma_f32_32x32x16_bf16 v[94:109], v[64:67], v[160:163], v[94:109]
	ds_read_b128 v[64:67], v156 offset:24576
	s_waitcnt lgkmcnt(1)
	v_mfma_f32_32x32x16_bf16 v[132:147], v[68:71], v[160:163], v[132:147]
	ds_read_b128 v[160:163], v164 offset:44032
	v_mfma_f32_32x32x16_bf16 v[110:125], v[68:71], v[152:155], v[110:125]
	ds_read_b128 v[152:155], v164 offset:41984
	v_mfma_f32_32x32x16_bf16 v[0:15], v[68:71], v[126:129], v[0:15]
	ds_read_b128 v[126:129], v164 offset:34816
	v_mfma_f32_32x32x16_bf16 v[16:31], v[68:71], v[72:75], v[16:31]
	ds_read_b128 v[72:75], v164 offset:32768
	ds_read_b128 v[68:71], v156 offset:26624
	s_waitcnt lgkmcnt(4)
	v_mfma_f32_32x32x16_bf16 v[94:109], v[64:67], v[160:163], v[94:109]
	s_waitcnt lgkmcnt(3)
	v_mfma_f32_32x32x16_bf16 v[78:93], v[64:67], v[152:155], v[78:93]
	s_waitcnt lgkmcnt(2)
	v_mfma_f32_32x32x16_bf16 v[32:47], v[64:67], v[126:129], v[32:47]
	s_waitcnt lgkmcnt(1)
	v_mfma_f32_32x32x16_bf16 v[48:63], v[64:67], v[72:75], v[48:63]
	s_waitcnt lgkmcnt(0)
	v_mfma_f32_32x32x16_bf16 v[16:31], v[68:71], v[72:75], v[16:31]
	v_mfma_f32_32x32x16_bf16 v[0:15], v[68:71], v[126:129], v[0:15]
	v_mfma_f32_32x32x16_bf16 v[110:125], v[68:71], v[152:155], v[110:125]
	v_mfma_f32_32x32x16_bf16 v[132:147], v[68:71], v[160:163], v[132:147]
	s_nop 7
	s_nop 7
	s_mov_b32 s32, 0
	s_lshl_b32 s9, s30, 7
	s_mov_b32 s10, s31
.Lg2a_epi:
	s_waitcnt lgkmcnt(0)
	s_barrier

.LBB0_1195:
	s_or_b64 exec, exec, s[2:3]
	v_mov_b32_e32 v150, v148
	s_mov_b32 s8, s55
	s_waitcnt lgkmcnt(0)
	s_barrier
	s_mov_b32 s9, s94
	s_cmpk_gt_i32 s8, 0x827
	s_cbranch_scc1 .LBB0_1224
	v_ashrrev_i32_e32 v151, 2, v150
	v_lshlrev_b32_e32 v0, 4, v150
	v_and_b32_e32 v128, 48, v0
	v_lshlrev_b32_e32 v0, 5, v151
	v_ashrrev_i32_e32 v1, 31, v0
	v_readlane_b32 s0, v158, 24
	v_mov_b32_e32 v131, 0
	v_lshlrev_b64 v[0:1], 1, v[0:1]
	v_readlane_b32 s1, v158, 25
	v_mov_b32_e32 v129, v131
	v_and_b32_e32 v5, 31, v150
	v_lshl_add_u64 v[2:3], s[0:1], 0, v[0:1]
	v_lshl_add_u64 v[134:135], v[2:3], 0, v[128:129]
	v_lshrrev_b32_e32 v3, 1, v150
	s_mov_b32 s1, 0xfffffc0
	s_movk_i32 s0, 0x50
	v_and_b32_e32 v4, 16, v3
	v_and_or_b32 v3, v3, s1, v5
	v_and_b32_e32 v5, 0x5f, v150
	v_mul_lo_u32 v2, v151, s0
	v_mul_lo_u32 v3, v3, s0
	v_mul_u32_u24_e32 v5, 0x50, v5
	s_add_u32 s0, s90, 0x22aa00
	v_lshl_add_u64 v[132:133], s[46:47], 0, v[128:129]
	s_addc_u32 s1, s91, 0
	v_lshl_add_u64 v[136:137], s[48:49], 0, v[0:1]
	s_movk_i32 s10, 0x2a00
	v_mov_b32_e32 v152, 0x60000
	s_mov_b32 s11, 0xa8000
	s_movk_i32 s12, 0x2000
	s_movk_i32 s13, 0x4000
	s_movk_i32 s14, 0x5000
	v_add_u32_e32 v153, v2, v128
	v_mov_b64_e32 v[138:139], s[46:47]
	v_add_u32_e32 v154, v4, v3
	v_add_u32_e32 v155, v4, v5
	s_mov_b32 s15, 0xa87000
	s_mov_b32 s16, 0xa89000
	s_mov_b32 s17, 0xa8b000
	s_mov_b64 s[2:3], 0x180
	s_mov_b64 s[4:5], 0xc000
	s_movk_i32 s18, 0x210
	v_and_b32_e32 v76, 63, v148
	v_lshrrev_b32_e32 v77, 6, v148
	v_and_b32_e32 v130, 31, v76
	v_lshlrev_b32_e32 v130, 6, v130
	v_lshrrev_b32_e32 v64, 5, v76
	v_bfe_u32 v65, v76, 2, 2
	v_xor_b32_e32 v64, v64, v65
	v_lshl_add_u32 v130, v64, 4, v130
	v_lshrrev_b32_e32 v64, 1, v77
	v_lshl_add_u32 v151, v64, 12, v130
	v_and_b32_e32 v64, 1, v77
	v_lshl_add_u32 v157, v64, 12, v130
	v_xor_b32_e32 v156, 32, v151
	v_xor_b32_e32 v164, 32, v157
	v_lshrrev_b32_e32 v130, 2, v76
	v_lshlrev_b32_e32 v130, 6, v130
	v_and_b32_e32 v64, 3, v76
	v_bfe_u32 v65, v76, 4, 2
	v_xor_b32_e32 v64, v64, v65
	v_lshl_add_u32 v130, v64, 4, v130
	v_lshl_add_u32 v165, v77, 11, v130
	v_lshrrev_b32_e32 v130, 2, v76
	v_lshl_add_u32 v130, v77, 5, v130
	v_mul_u32_u24_e32 v130, 0x2a00, v130
	v_and_b32_e32 v64, 3, v76
	v_bfe_u32 v65, v76, 4, 2
	v_xor_b32_e32 v64, v64, v65
	v_lshl_add_u32 v166, v64, 4, v130
	v_add_u32_e32 v167, 0x2a000, v166
	v_readfirstlane_b32 s28, v77
	s_lshl_b32 s28, s28, 11
	s_and_b32 s33, s8, 7
	s_lshr_b32 s8, s8, 3
	s_lshr_b32 s56, s9, 3
	s_sub_u32 s57, 268, s33
	s_lshr_b32 s57, s57, 3
	s_mul_i32 s57, s57, 4
	s_branch .Lg2b_hdr
.LBB0_1197:
	s_or_b64 exec, exec, s[6:7]
	s_cmp_eq_u32 s32, 0
	s_cbranch_scc1 .Lg2b_pass2
	s_add_i32 s8, s8, s56
	s_cmp_lt_u32 s8, s57
	s_cbranch_scc0 .LBB0_1224
	s_branch .Lg2b_hdr
.Lg2b_pass2:
	s_mov_b32 s32, 1
	v_mov_b32_e32 v48, v78
	v_mov_b32_e32 v49, v79
	v_mov_b32_e32 v50, v80
	v_mov_b32_e32 v51, v81
	v_mov_b32_e32 v52, v82
	v_mov_b32_e32 v53, v83
	v_mov_b32_e32 v54, v84
	v_mov_b32_e32 v55, v85
	v_mov_b32_e32 v56, v86
	v_mov_b32_e32 v57, v87
	v_mov_b32_e32 v58, v88
	v_mov_b32_e32 v59, v89
	v_mov_b32_e32 v60, v90
	v_mov_b32_e32 v61, v91
	v_mov_b32_e32 v62, v92
	v_mov_b32_e32 v63, v93
	v_mov_b32_e32 v32, v94
	v_mov_b32_e32 v33, v95
	v_mov_b32_e32 v34, v96
	v_mov_b32_e32 v35, v97
	v_mov_b32_e32 v36, v98
	v_mov_b32_e32 v37, v99
	v_mov_b32_e32 v38, v100
	v_mov_b32_e32 v39, v101
	v_mov_b32_e32 v40, v102
	v_mov_b32_e32 v41, v103
	v_mov_b32_e32 v42, v104
	v_mov_b32_e32 v43, v105
	v_mov_b32_e32 v44, v106
	v_mov_b32_e32 v45, v107
	v_mov_b32_e32 v46, v108
	v_mov_b32_e32 v47, v109
	v_mov_b32_e32 v16, v110
	v_mov_b32_e32 v17, v111
	v_mov_b32_e32 v18, v112
	v_mov_b32_e32 v19, v113
	v_mov_b32_e32 v20, v114
	v_mov_b32_e32 v21, v115
	v_mov_b32_e32 v22, v116
	v_mov_b32_e32 v23, v117
	v_mov_b32_e32 v24, v118
	v_mov_b32_e32 v25, v119
	v_mov_b32_e32 v26, v120
	v_mov_b32_e32 v27, v121
	v_mov_b32_e32 v28, v122
	v_mov_b32_e32 v29, v123
	v_mov_b32_e32 v30, v124
	v_mov_b32_e32 v31, v125
	v_mov_b32_e32 v0, v132
	v_mov_b32_e32 v1, v133
	v_mov_b32_e32 v2, v134
	v_mov_b32_e32 v3, v135
	v_mov_b32_e32 v4, v136
	v_mov_b32_e32 v5, v137
	v_mov_b32_e32 v6, v138
	v_mov_b32_e32 v7, v139
	v_mov_b32_e32 v8, v140
	v_mov_b32_e32 v9, v141
	v_mov_b32_e32 v10, v142
	v_mov_b32_e32 v11, v143
	v_mov_b32_e32 v12, v144
	v_mov_b32_e32 v13, v145
	v_mov_b32_e32 v14, v146
	v_mov_b32_e32 v15, v147
	s_lshl_b32 s19, s30, 7
	s_add_i32 s20, s31, 1
	s_branch .Lg2b_epi
.Lg2b_hdr:
	s_cmp_ge_u32 s8, 128
	s_cbranch_scc1 .Lg2b_lastgrp
	s_mul_hi_u32 s2, s8, 0x4000000
	s_mul_i32 s3, s2, 64
	s_sub_i32 s3, s8, s3
	s_lshr_b32 s6, s3, 4
	s_and_b32 s5, s3, 15
	s_lshl4_add_u32 s5, s2, s5
	s_branch .Lg2b_cont
.Lg2b_lastgrp:
	s_sub_u32 s3, s8, 128
	s_mul_hi_u32 s2, s3, 0x40000000
	s_mul_i32 s6, s2, 4
	s_sub_i32 s6, s3, s6
	s_add_u32 s5, s2, 32
.Lg2b_cont:
	s_lshl3_add_u32 s30, s5, s33
	s_lshl_b32 s31, s6, 1
	s_mul_i32 s2, s30, 0x150000
	s_add_u32 s22, s46, s2
	s_addc_u32 s23, s47, 0
	s_mul_i32 s2, s31, 0x60000
	s_add_u32 s2, s2, 0xa80000
	s_add_u32 s24, s48, s2
	s_addc_u32 s25, s49, 0
	s_add_u32 s26, s24, 0x60000
	s_addc_u32 s27, s25, 0
	s_waitcnt vmcnt(0) lgkmcnt(0)
	s_barrier
	s_add_u32 m0, s28, 0x0
	s_nop 0
	global_load_lds_dwordx4 v166, s[22:23]
	s_add_u32 m0, s28, 0x400
	s_nop 0
	global_load_lds_dwordx4 v167, s[22:23]
	s_add_u32 s22, s22, 64
	s_addc_u32 s23, s23, 0
	s_add_u32 m0, s28, 0x2000
	s_nop 0
	global_load_lds_dwordx4 v165, s[24:25]
	global_load_lds_dwordx4 v165, s[24:25] offset:1024
	s_add_u32 s24, s24, 0x2000
	s_addc_u32 s25, s25, 0
	s_add_u32 m0, s28, 0x4000
	s_nop 0
	global_load_lds_dwordx4 v165, s[26:27]
	global_load_lds_dwordx4 v165, s[26:27] offset:1024
	s_add_u32 s26, s26, 0x2000
	s_addc_u32 s27, s27, 0
	s_waitcnt vmcnt(0)
	s_barrier
	s_add_u32 m0, s28, 0x6000
	s_nop 0
	global_load_lds_dwordx4 v166, s[22:23]
	s_add_u32 m0, s28, 0x6400
	s_nop 0
	global_load_lds_dwordx4 v167, s[22:23]
	s_add_u32 s22, s22, 64
	s_addc_u32 s23, s23, 0
	s_add_u32 m0, s28, 0x8000
	s_nop 0
	global_load_lds_dwordx4 v165, s[24:25]
	global_load_lds_dwordx4 v165, s[24:25] offset:1024
	s_add_u32 s24, s24, 0x2000
	s_addc_u32 s25, s25, 0
	s_add_u32 m0, s28, 0xa400
	s_nop 0
	global_load_lds_dwordx4 v165, s[26:27]
	global_load_lds_dwordx4 v165, s[26:27] offset:1024
	s_add_u32 s26, s26, 0x2000
	s_addc_u32 s27, s27, 0
	ds_read_b128 v[64:67], v151 offset:0
	ds_read_b128 v[72:75], v157 offset:8192
	ds_read_b128 v[126:129], v157 offset:10240
	ds_read_b128 v[152:155], v157 offset:16384
	ds_read_b128 v[160:163], v157 offset:18432
	ds_read_b128 v[68:71], v151 offset:2048
	s_waitcnt lgkmcnt(4)
	v_mfma_f32_32x32x16_bf16 v[48:63], v[64:67], v[72:75], 0
	s_waitcnt lgkmcnt(3)
	v_mfma_f32_32x32x16_bf16 v[32:47], v[64:67], v[126:129], 0
	s_waitcnt lgkmcnt(2)
	v_mfma_f32_32x32x16_bf16 v[78:93], v[64:67], v[152:155], 0
	s_waitcnt lgkmcnt(1)
	v_mfma_f32_32x32x16_bf16 v[94:109], v[64:67], v[160:163], 0
	ds_read_b128 v[64:67], v156 offset:0
	s_waitcnt lgkmcnt(1)
	v_mfma_f32_32x32x16_bf16 v[132:147], v[68:71], v[160:163], 0
	ds_read_b128 v[160:163], v164 offset:18432
	v_mfma_f32_32x32x16_bf16 v[110:125], v[68:71], v[152:155], 0
	ds_read_b128 v[152:155], v164 offset:16384
	v_mfma_f32_32x32x16_bf16 v[0:15], v[68:71], v[126:129], 0
	ds_read_b128 v[126:129], v164 offset:10240
	v_mfma_f32_32x32x16_bf16 v[16:31], v[68:71], v[72:75], 0
	ds_read_b128 v[72:75], v164 offset:8192
	ds_read_b128 v[68:71], v156 offset:2048
	s_waitcnt lgkmcnt(4)
	v_mfma_f32_32x32x16_bf16 v[94:109], v[64:67], v[160:163], v[94:109]
	s_waitcnt lgkmcnt(3)
	v_mfma_f32_32x32x16_bf16 v[78:93], v[64:67], v[152:155], v[78:93]
	s_waitcnt lgkmcnt(2)
	v_mfma_f32_32x32x16_bf16 v[32:47], v[64:67], v[126:129], v[32:47]
	s_waitcnt lgkmcnt(1)
	v_mfma_f32_32x32x16_bf16 v[48:63], v[64:67], v[72:75], v[48:63]
	s_waitcnt vmcnt(0) lgkmcnt(0)
	s_barrier
	ds_read_b128 v[64:67], v151 offset:24576
	s_add_u32 m0, s28, 0x0
	s_nop 0
	global_load_lds_dwordx4 v166, s[22:23]
	s_add_u32 m0, s28, 0x400
	s_nop 0
	global_load_lds_dwordx4 v167, s[22:23]
	s_add_u32 s22, s22, 64
	s_addc_u32 s23, s23, 0
	v_mfma_f32_32x32x16_bf16 v[16:31], v[68:71], v[72:75], v[16:31]
	ds_read_b128 v[72:75], v157 offset:32768
	s_add_u32 m0, s28, 0x2000
	s_nop 0
	global_load_lds_dwordx4 v165, s[24:25]
	global_load_lds_dwordx4 v165, s[24:25] offset:1024
	s_add_u32 s24, s24, 0x2000
	s_addc_u32 s25, s25, 0
	v_mfma_f32_32x32x16_bf16 v[0:15], v[68:71], v[126:129], v[0:15]
	ds_read_b128 v[126:129], v157 offset:34816
	s_add_u32 m0, s28, 0x4000
	s_nop 0
	global_load_lds_dwordx4 v165, s[26:27]
	global_load_lds_dwordx4 v165, s[26:27] offset:1024
	s_add_u32 s26, s26, 0x2000
	s_addc_u32 s27, s27, 0
	v_mfma_f32_32x32x16_bf16 v[110:125], v[68:71], v[152:155], v[110:125]
	ds_read_b128 v[152:155], v157 offset:41984
	v_mfma_f32_32x32x16_bf16 v[132:147], v[68:71], v[160:163], v[132:147]
	ds_read_b128 v[160:163], v157 offset:44032
	ds_read_b128 v[68:71], v151 offset:26624
	s_waitcnt lgkmcnt(4)
	v_mfma_f32_32x32x16_bf16 v[48:63], v[64:67], v[72:75], v[48:63]
	s_waitcnt lgkmcnt(3)
	v_mfma_f32_32x32x16_bf16 v[32:47], v[64:67], v[126:129], v[32:47]
	s_waitcnt lgkmcnt(2)
	v_mfma_f32_32x32x16_bf16 v[78:93], v[64:67], v[152:155], v[78:93]
	s_waitcnt lgkmcnt(1)
	v_mfma_f32_32x32x16_bf16 v[94:109], v[64:67], v[160:163], v[94:109]
	ds_read_b128 v[64:67], v156 offset:24576
	s_waitcnt lgkmcnt(1)
	v_mfma_f32_32x32x16_bf16 v[132:147], v[68:71], v[160:163], v[132:147]
	ds_read_b128 v[160:163], v164 offset:44032
	v_mfma_f32_32x32x16_bf16 v[110:125], v[68:71], v[152:155], v[110:125]
	ds_read_b128 v[152:155], v164 offset:41984
	v_mfma_f32_32x32x16_bf16 v[0:15], v[68:71], v[126:129], v[0:15]
	ds_read_b128 v[126:129], v164 offset:34816
	v_mfma_f32_32x32x16_bf16 v[16:31], v[68:71], v[72:75], v[16:31]
	ds_read_b128 v[72:75], v164 offset:32768
	ds_read_b128 v[68:71], v156 offset:26624
	s_waitcnt lgkmcnt(4)
	v_mfma_f32_32x32x16_bf16 v[94:109], v[64:67], v[160:163], v[94:109]
	s_waitcnt lgkmcnt(3)
	v_mfma_f32_32x32x16_bf16 v[78:93], v[64:67], v[152:155], v[78:93]
	s_waitcnt lgkmcnt(2)
	v_mfma_f32_32x32x16_bf16 v[32:47], v[64:67], v[126:129], v[32:47]
	s_waitcnt lgkmcnt(1)
	v_mfma_f32_32x32x16_bf16 v[48:63], v[64:67], v[72:75], v[48:63]
	s_waitcnt vmcnt(0) lgkmcnt(0)
	s_barrier
	ds_read_b128 v[64:67], v151 offset:0
	s_add_u32 m0, s28, 0x6000
	s_nop 0
	global_load_lds_dwordx4 v166, s[22:23]
	s_add_u32 m0, s28, 0x6400
	s_nop 0
	global_load_lds_dwordx4 v167, s[22:23]
	s_add_u32 s22, s22, 64
	s_addc_u32 s23, s23, 0
	v_mfma_f32_32x32x16_bf16 v[16:31], v[68:71], v[72:75], v[16:31]
	ds_read_b128 v[72:75], v157 offset:8192
	s_add_u32 m0, s28, 0x8000
	s_nop 0
	global_load_lds_dwordx4 v165, s[24:25]
	global_load_lds_dwordx4 v165, s[24:25] offset:1024
	s_add_u32 s24, s24, 0x2000
	s_addc_u32 s25, s25, 0
	v_mfma_f32_32x32x16_bf16 v[0:15], v[68:71], v[126:129], v[0:15]
	ds_read_b128 v[126:129], v157 offset:10240
	s_add_u32 m0, s28, 0xa400
	s_nop 0
	global_load_lds_dwordx4 v165, s[26:27]
	global_load_lds_dwordx4 v165, s[26:27] offset:1024
	s_add_u32 s26, s26, 0x2000
	s_addc_u32 s27, s27, 0
	v_mfma_f32_32x32x16_bf16 v[110:125], v[68:71], v[152:155], v[110:125]
	ds_read_b128 v[152:155], v157 offset:16384
	v_mfma_f32_32x32x16_bf16 v[132:147], v[68:71], v[160:163], v[132:147]
	ds_read_b128 v[160:163], v157 offset:18432
	ds_read_b128 v[68:71], v151 offset:2048
	s_mov_b32 s29, 22
.Lg2b_kloop:
	s_waitcnt lgkmcnt(4)
	v_mfma_f32_32x32x16_bf16 v[48:63], v[64:67], v[72:75], v[48:63]
	s_waitcnt lgkmcnt(3)
	v_mfma_f32_32x32x16_bf16 v[32:47], v[64:67], v[126:129], v[32:47]
	s_waitcnt lgkmcnt(2)
	v_mfma_f32_32x32x16_bf16 v[78:93], v[64:67], v[152:155], v[78:93]
	s_waitcnt lgkmcnt(1)
	v_mfma_f32_32x32x16_bf16 v[94:109], v[64:67], v[160:163], v[94:109]
	ds_read_b128 v[64:67], v156 offset:0
	s_waitcnt lgkmcnt(1)
	v_mfma_f32_32x32x16_bf16 v[132:147], v[68:71], v[160:163], v[132:147]
	ds_read_b128 v[160:163], v164 offset:18432
	v_mfma_f32_32x32x16_bf16 v[110:125], v[68:71], v[152:155], v[110:125]
	ds_read_b128 v[152:155], v164 offset:16384
	v_mfma_f32_32x32x16_bf16 v[0:15], v[68:71], v[126:129], v[0:15]
	ds_read_b128 v[126:129], v164 offset:10240
	v_mfma_f32_32x32x16_bf16 v[16:31], v[68:71], v[72:75], v[16:31]
	ds_read_b128 v[72:75], v164 offset:8192
	ds_read_b128 v[68:71], v156 offset:2048
	s_waitcnt lgkmcnt(4)
	v_mfma_f32_32x32x16_bf16 v[94:109], v[64:67], v[160:163], v[94:109]
	s_waitcnt lgkmcnt(3)
	v_mfma_f32_32x32x16_bf16 v[78:93], v[64:67], v[152:155], v[78:93]
	s_waitcnt lgkmcnt(2)
	v_mfma_f32_32x32x16_bf16 v[32:47], v[64:67], v[126:129], v[32:47]
	s_waitcnt lgkmcnt(1)
	v_mfma_f32_32x32x16_bf16 v[48:63], v[64:67], v[72:75], v[48:63]
	s_waitcnt vmcnt(0) lgkmcnt(0)
	s_barrier
	ds_read_b128 v[64:67], v151 offset:24576
	s_add_u32 m0, s28, 0x0
	s_nop 0
	global_load_lds_dwordx4 v166, s[22:23]
	s_add_u32 m0, s28, 0x400
	s_nop 0
	global_load_lds_dwordx4 v167, s[22:23]
	s_add_u32 s22, s22, 64
	s_addc_u32 s23, s23, 0
	v_mfma_f32_32x32x16_bf16 v[16:31], v[68:71], v[72:75], v[16:31]
	ds_read_b128 v[72:75], v157 offset:32768
	s_add_u32 m0, s28, 0x2000
	s_nop 0
	global_load_lds_dwordx4 v165, s[24:25]
	global_load_lds_dwordx4 v165, s[24:25] offset:1024
	s_add_u32 s24, s24, 0x2000
	s_addc_u32 s25, s25, 0
	v_mfma_f32_32x32x16_bf16 v[0:15], v[68:71], v[126:129], v[0:15]
	ds_read_b128 v[126:129], v157 offset:34816
	s_add_u32 m0, s28, 0x4000
	s_nop 0
	global_load_lds_dwordx4 v165, s[26:27]
	global_load_lds_dwordx4 v165, s[26:27] offset:1024
	s_add_u32 s26, s26, 0x2000
	s_addc_u32 s27, s27, 0
	v_mfma_f32_32x32x16_bf16 v[110:125], v[68:71], v[152:155], v[110:125]
	ds_read_b128 v[152:155], v157 offset:41984
	v_mfma_f32_32x32x16_bf16 v[132:147], v[68:71], v[160:163], v[132:147]
	ds_read_b128 v[160:163], v157 offset:44032
	ds_read_b128 v[68:71], v151 offset:26624
	s_waitcnt lgkmcnt(4)
	v_mfma_f32_32x32x16_bf16 v[48:63], v[64:67], v[72:75], v[48:63]
	s_waitcnt lgkmcnt(3)
	v_mfma_f32_32x32x16_bf16 v[32:47], v[64:67], v[126:129], v[32:47]
	s_waitcnt lgkmcnt(2)
	v_mfma_f32_32x32x16_bf16 v[78:93], v[64:67], v[152:155], v[78:93]
	s_waitcnt lgkmcnt(1)
	v_mfma_f32_32x32x16_bf16 v[94:109], v[64:67], v[160:163], v[94:109]
	ds_read_b128 v[64:67], v156 offset:24576
	s_waitcnt lgkmcnt(1)
	v_mfma_f32_32x32x16_bf16 v[132:147], v[68:71], v[160:163], v[132:147]
	ds_read_b128 v[160:163], v164 offset:44032
	v_mfma_f32_32x32x16_bf16 v[110:125], v[68:71], v[152:155], v[110:125]
	ds_read_b128 v[152:155], v164 offset:41984
	v_mfma_f32_32x32x16_bf16 v[0:15], v[68:71], v[126:129], v[0:15]
	ds_read_b128 v[126:129], v164 offset:34816
	v_mfma_f32_32x32x16_bf16 v[16:31], v[68:71], v[72:75], v[16:31]
	ds_read_b128 v[72:75], v164 offset:32768
	ds_read_b128 v[68:71], v156 offset:26624
	s_waitcnt lgkmcnt(4)
	v_mfma_f32_32x32x16_bf16 v[94:109], v[64:67], v[160:163], v[94:109]
	s_waitcnt lgkmcnt(3)
	v_mfma_f32_32x32x16_bf16 v[78:93], v[64:67], v[152:155], v[78:93]
	s_waitcnt lgkmcnt(2)
	v_mfma_f32_32x32x16_bf16 v[32:47], v[64:67], v[126:129], v[32:47]
	s_waitcnt lgkmcnt(1)
	v_mfma_f32_32x32x16_bf16 v[48:63], v[64:67], v[72:75], v[48:63]
	s_waitcnt vmcnt(0) lgkmcnt(0)
	s_barrier
	ds_read_b128 v[64:67], v151 offset:0
	s_add_u32 m0, s28, 0x6000
	s_nop 0
	global_load_lds_dwordx4 v166, s[22:23]
	s_add_u32 m0, s28, 0x6400
	s_nop 0
	global_load_lds_dwordx4 v167, s[22:23]
	s_add_u32 s22, s22, 64
	s_addc_u32 s23, s23, 0
	v_mfma_f32_32x32x16_bf16 v[16:31], v[68:71], v[72:75], v[16:31]
	ds_read_b128 v[72:75], v157 offset:8192
	s_add_u32 m0, s28, 0x8000
	s_nop 0
	global_load_lds_dwordx4 v165, s[24:25]
	global_load_lds_dwordx4 v165, s[24:25] offset:1024
	s_add_u32 s24, s24, 0x2000
	s_addc_u32 s25, s25, 0
	v_mfma_f32_32x32x16_bf16 v[0:15], v[68:71], v[126:129], v[0:15]
	ds_read_b128 v[126:129], v157 offset:10240
	s_add_u32 m0, s28, 0xa400
	s_nop 0
	global_load_lds_dwordx4 v165, s[26:27]
	global_load_lds_dwordx4 v165, s[26:27] offset:1024
	s_add_u32 s26, s26, 0x2000
	s_addc_u32 s27, s27, 0
	v_mfma_f32_32x32x16_bf16 v[110:125], v[68:71], v[152:155], v[110:125]
	ds_read_b128 v[152:155], v157 offset:16384
	v_mfma_f32_32x32x16_bf16 v[132:147], v[68:71], v[160:163], v[132:147]
	ds_read_b128 v[160:163], v157 offset:18432
	ds_read_b128 v[68:71], v151 offset:2048
	s_sub_u32 s29, s29, 1
	s_cmp_lg_u32 s29, 0
	s_cbranch_scc1 .Lg2b_kloop
	s_waitcnt lgkmcnt(4)
	v_mfma_f32_32x32x16_bf16 v[48:63], v[64:67], v[72:75], v[48:63]
	s_waitcnt lgkmcnt(3)
	v_mfma_f32_32x32x16_bf16 v[32:47], v[64:67], v[126:129], v[32:47]
	s_waitcnt lgkmcnt(2)
	v_mfma_f32_32x32x16_bf16 v[78:93], v[64:67], v[152:155], v[78:93]
	s_waitcnt lgkmcnt(1)
	v_mfma_f32_32x32x16_bf16 v[94:109], v[64:67], v[160:163], v[94:109]
	ds_read_b128 v[64:67], v156 offset:0
	s_waitcnt lgkmcnt(1)
	v_mfma_f32_32x32x16_bf16 v[132:147], v[68:71], v[160:163], v[132:147]
	ds_read_b128 v[160:163], v164 offset:18432
	v_mfma_f32_32x32x16_bf16 v[110:125], v[68:71], v[152:155], v[110:125]
	ds_read_b128 v[152:155], v164 offset:16384
	v_mfma_f32_32x32x16_bf16 v[0:15], v[68:71], v[126:129], v[0:15]
	ds_read_b128 v[126:129], v164 offset:10240
	v_mfma_f32_32x32x16_bf16 v[16:31], v[68:71], v[72:75], v[16:31]
	ds_read_b128 v[72:75], v164 offset:8192
	ds_read_b128 v[68:71], v156 offset:2048
	s_waitcnt lgkmcnt(4)
	v_mfma_f32_32x32x16_bf16 v[94:109], v[64:67], v[160:163], v[94:109]
	s_waitcnt lgkmcnt(3)
	v_mfma_f32_32x32x16_bf16 v[78:93], v[64:67], v[152:155], v[78:93]
	s_waitcnt lgkmcnt(2)
	v_mfma_f32_32x32x16_bf16 v[32:47], v[64:67], v[126:129], v[32:47]
	s_waitcnt lgkmcnt(1)
	v_mfma_f32_32x32x16_bf16 v[48:63], v[64:67], v[72:75], v[48:63]
	s_waitcnt vmcnt(0) lgkmcnt(0)
	s_barrier
	ds_read_b128 v[64:67], v151 offset:24576
	v_mfma_f32_32x32x16_bf16 v[16:31], v[68:71], v[72:75], v[16:31]
	ds_read_b128 v[72:75], v157 offset:32768
	v_mfma_f32_32x32x16_bf16 v[0:15], v[68:71], v[126:129], v[0:15]
	ds_read_b128 v[126:129], v157 offset:34816
	v_mfma_f32_32x32x16_bf16 v[110:125], v[68:71], v[152:155], v[110:125]
	ds_read_b128 v[152:155], v157 offset:41984
	v_mfma_f32_32x32x16_bf16 v[132:147], v[68:71], v[160:163], v[132:147]
	ds_read_b128 v[160:163], v157 offset:44032
	ds_read_b128 v[68:71], v151 offset:26624
	s_waitcnt lgkmcnt(4)
	v_mfma_f32_32x32x16_bf16 v[48:63], v[64:67], v[72:75], v[48:63]
	s_waitcnt lgkmcnt(3)
	v_mfma_f32_32x32x16_bf16 v[32:47], v[64:67], v[126:129], v[32:47]
	s_waitcnt lgkmcnt(2)
	v_mfma_f32_32x32x16_bf16 v[78:93], v[64:67], v[152:155], v[78:93]
	s_waitcnt lgkmcnt(1)
	v_mfma_f32_32x32x16_bf16 v[94:109], v[64:67], v[160:163], v[94:109]
	ds_read_b128 v[64:67], v156 offset:24576
	s_waitcnt lgkmcnt(1)
	v_mfma_f32_32x32x16_bf16 v[132:147], v[68:71], v[160:163], v[132:147]
	ds_read_b128 v[160:163], v164 offset:44032
	v_mfma_f32_32x32x16_bf16 v[110:125], v[68:71], v[152:155], v[110:125]
	ds_read_b128 v[152:155], v164 offset:41984
	v_mfma_f32_32x32x16_bf16 v[0:15], v[68:71], v[126:129], v[0:15]
	ds_read_b128 v[126:129], v164 offset:34816
	v_mfma_f32_32x32x16_bf16 v[16:31], v[68:71], v[72:75], v[16:31]
	ds_read_b128 v[72:75], v164 offset:32768
	ds_read_b128 v[68:71], v156 offset:26624
	s_waitcnt lgkmcnt(4)
	v_mfma_f32_32x32x16_bf16 v[94:109], v[64:67], v[160:163], v[94:109]
	s_waitcnt lgkmcnt(3)
	v_mfma_f32_32x32x16_bf16 v[78:93], v[64:67], v[152:155], v[78:93]
	s_waitcnt lgkmcnt(2)
	v_mfma_f32_32x32x16_bf16 v[32:47], v[64:67], v[126:129], v[32:47]
	s_waitcnt lgkmcnt(1)
	v_mfma_f32_32x32x16_bf16 v[48:63], v[64:67], v[72:75], v[48:63]
	s_waitcnt lgkmcnt(0)
	v_mfma_f32_32x32x16_bf16 v[16:31], v[68:71], v[72:75], v[16:31]
	v_mfma_f32_32x32x16_bf16 v[0:15], v[68:71], v[126:129], v[0:15]
	v_mfma_f32_32x32x16_bf16 v[110:125], v[68:71], v[152:155], v[110:125]
	v_mfma_f32_32x32x16_bf16 v[132:147], v[68:71], v[160:163], v[132:147]
	s_nop 7
	s_nop 7
	s_mov_b32 s32, 0
	s_lshl_b32 s19, s30, 7
	s_mov_b32 s20, s31
